# phase-0 rmsnorm(x): hand-written software-pipelined loop (row pair two trips ahead loaded before stores; 16 KB per wave in flight) on top of v067
# baseline (speedup 1.0000x reference)
.LBB0_101:
	s_or_b64 exec, exec, s[0:1]
	v_mov_b32_e32 v47, 0
	v_lshlrev_b32_e32 v46, 3, v193
	s_cmp_lg_u32 s33, 0x800
	s_cbranch_scc1 .Lrn_generic
	v_readfirstlane_b32 s8, v192
	v_lshlrev_b32_e32 v34, 4, v193
	global_load_dwordx4 v[2:5], v34, s[42:43] offset:3072
	global_load_dwordx4 v[6:9], v34, s[42:43] offset:2048
	global_load_dwordx4 v[10:13], v34, s[42:43] offset:1024
	global_load_dwordx4 v[14:17], v34, s[42:43]
	s_lshl_b32 s9, s8, 12
	s_add_u32 s0, s36, s9
	s_addc_u32 s1, s37, 0
	s_lshl_b32 s9, s8, 11
	s_add_u32 s2, s68, s9
	s_addc_u32 s3, s69, 0
	global_load_dwordx4 v[80:83], v34, s[0:1]
	global_load_dwordx4 v[84:87], v34, s[0:1] offset:1024
	global_load_dwordx4 v[88:91], v34, s[0:1] offset:2048
	global_load_dwordx4 v[92:95], v34, s[0:1] offset:3072
	s_add_u32 s0, s0, 0x800000
	s_addc_u32 s1, s1, 0
	global_load_dwordx4 v[96:99], v34, s[0:1]
	global_load_dwordx4 v[100:103], v34, s[0:1] offset:1024
	global_load_dwordx4 v[104:107], v34, s[0:1] offset:2048
	global_load_dwordx4 v[108:111], v34, s[0:1] offset:3072
	s_add_u32 s0, s0, 0x800000
	s_addc_u32 s1, s1, 0
	global_load_dwordx4 v[208:211], v34, s[0:1]
	global_load_dwordx4 v[212:215], v34, s[0:1] offset:1024
	global_load_dwordx4 v[216:219], v34, s[0:1] offset:2048
	global_load_dwordx4 v[220:223], v34, s[0:1] offset:3072
	s_add_u32 s0, s0, 0x800000
	s_addc_u32 s1, s1, 0
	global_load_dwordx4 v[224:227], v34, s[0:1]
	global_load_dwordx4 v[228:231], v34, s[0:1] offset:1024
	global_load_dwordx4 v[232:235], v34, s[0:1] offset:2048
	global_load_dwordx4 v[236:239], v34, s[0:1] offset:3072
	s_add_u32 s0, s0, 0x800000
	s_addc_u32 s1, s1, 0
	v_xor_b32_e32 v35, 1, v193
	v_xor_b32_e32 v36, 2, v193
	v_xor_b32_e32 v37, 4, v193
	v_xor_b32_e32 v38, 8, v193
	v_xor_b32_e32 v39, 16, v193
	v_xor_b32_e32 v40, 32, v193
	v_lshlrev_b32_e32 v35, 2, v35
	v_lshlrev_b32_e32 v36, 2, v36
	v_lshlrev_b32_e32 v37, 2, v37
	v_lshlrev_b32_e32 v38, 2, v38
	v_lshlrev_b32_e32 v39, 2, v39
	v_lshlrev_b32_e32 v40, 2, v40
	s_mov_b32 s10, 0x3a800000
	v_mov_b32_e32 v52, 0x358637bd
	s_waitcnt vmcnt(8)
	v_pk_mul_f32 v[60:61], v[80:81], v[80:81]
	v_pk_mul_f32 v[62:63], v[82:83], v[82:83]
	v_pk_mul_f32 v[68:69], v[96:97], v[96:97]
	v_pk_mul_f32 v[70:71], v[98:99], v[98:99]
	v_pk_fma_f32 v[60:61], v[84:85], v[84:85], v[60:61]
	v_pk_fma_f32 v[62:63], v[86:87], v[86:87], v[62:63]
	v_pk_fma_f32 v[68:69], v[100:101], v[100:101], v[68:69]
	v_pk_fma_f32 v[70:71], v[102:103], v[102:103], v[70:71]
	v_pk_fma_f32 v[60:61], v[88:89], v[88:89], v[60:61]
	v_pk_fma_f32 v[62:63], v[90:91], v[90:91], v[62:63]
	v_pk_fma_f32 v[68:69], v[104:105], v[104:105], v[68:69]
	v_pk_fma_f32 v[70:71], v[106:107], v[106:107], v[70:71]
	v_pk_fma_f32 v[60:61], v[92:93], v[92:93], v[60:61]
	v_pk_fma_f32 v[62:63], v[94:95], v[94:95], v[62:63]
	v_pk_fma_f32 v[68:69], v[108:109], v[108:109], v[68:69]
	v_pk_fma_f32 v[70:71], v[110:111], v[110:111], v[70:71]
	v_pk_add_f32 v[60:61], v[60:61], v[62:63]
	v_pk_add_f32 v[68:69], v[68:69], v[70:71]
	v_add_f32_e32 v60, v60, v61
	v_add_f32_e32 v61, v68, v69
	ds_bpermute_b32 v62, v35, v60
	ds_bpermute_b32 v63, v35, v61
	s_waitcnt lgkmcnt(0)
	v_pk_add_f32 v[60:61], v[60:61], v[62:63]
	ds_bpermute_b32 v62, v36, v60
	ds_bpermute_b32 v63, v36, v61
	s_waitcnt lgkmcnt(0)
	v_pk_add_f32 v[60:61], v[60:61], v[62:63]
	ds_bpermute_b32 v62, v37, v60
	ds_bpermute_b32 v63, v37, v61
	s_waitcnt lgkmcnt(0)
	v_pk_add_f32 v[60:61], v[60:61], v[62:63]
	ds_bpermute_b32 v62, v38, v60
	ds_bpermute_b32 v63, v38, v61
	s_waitcnt lgkmcnt(0)
	v_pk_add_f32 v[60:61], v[60:61], v[62:63]
	ds_bpermute_b32 v62, v39, v60
	ds_bpermute_b32 v63, v39, v61
	s_waitcnt lgkmcnt(0)
	v_pk_add_f32 v[60:61], v[60:61], v[62:63]
	ds_bpermute_b32 v62, v40, v60
	ds_bpermute_b32 v63, v40, v61
	s_waitcnt lgkmcnt(0)
	v_pk_add_f32 v[60:61], v[60:61], v[62:63]
	v_fma_f32 v60, v60, s10, v52
	v_fma_f32 v62, v61, s10, v52
	v_rsq_f32_e32 v60, v60
	v_rsq_f32_e32 v62, v62
	s_nop 0
	v_pk_mul_f32 v[80:81], v[80:81], v[60:61] op_sel_hi:[1,0]
	v_pk_mul_f32 v[82:83], v[82:83], v[60:61] op_sel_hi:[1,0]
	v_pk_mul_f32 v[80:81], v[14:15], v[80:81]
	v_pk_mul_f32 v[82:83], v[16:17], v[82:83]
	v_cvt_pk_bf16_f32 v18, v80, v81
	v_cvt_pk_bf16_f32 v19, v82, v83
	v_pk_mul_f32 v[84:85], v[84:85], v[60:61] op_sel_hi:[1,0]
	v_pk_mul_f32 v[86:87], v[86:87], v[60:61] op_sel_hi:[1,0]
	v_pk_mul_f32 v[84:85], v[10:11], v[84:85]
	v_pk_mul_f32 v[86:87], v[12:13], v[86:87]
	v_cvt_pk_bf16_f32 v20, v84, v85
	v_cvt_pk_bf16_f32 v21, v86, v87
	v_pk_mul_f32 v[88:89], v[88:89], v[60:61] op_sel_hi:[1,0]
	v_pk_mul_f32 v[90:91], v[90:91], v[60:61] op_sel_hi:[1,0]
	v_pk_mul_f32 v[88:89], v[6:7], v[88:89]
	v_pk_mul_f32 v[90:91], v[8:9], v[90:91]
	v_cvt_pk_bf16_f32 v22, v88, v89
	v_cvt_pk_bf16_f32 v23, v90, v91
	v_pk_mul_f32 v[92:93], v[92:93], v[60:61] op_sel_hi:[1,0]
	v_pk_mul_f32 v[94:95], v[94:95], v[60:61] op_sel_hi:[1,0]
	v_pk_mul_f32 v[92:93], v[2:3], v[92:93]
	v_pk_mul_f32 v[94:95], v[4:5], v[94:95]
	v_cvt_pk_bf16_f32 v24, v92, v93
	v_cvt_pk_bf16_f32 v25, v94, v95
	v_pk_mul_f32 v[96:97], v[96:97], v[62:63] op_sel_hi:[1,0]
	v_pk_mul_f32 v[98:99], v[98:99], v[62:63] op_sel_hi:[1,0]
	v_pk_mul_f32 v[96:97], v[14:15], v[96:97]
	v_pk_mul_f32 v[98:99], v[16:17], v[98:99]
	v_cvt_pk_bf16_f32 v26, v96, v97
	v_cvt_pk_bf16_f32 v27, v98, v99
	v_pk_mul_f32 v[100:101], v[100:101], v[62:63] op_sel_hi:[1,0]
	v_pk_mul_f32 v[102:103], v[102:103], v[62:63] op_sel_hi:[1,0]
	v_pk_mul_f32 v[100:101], v[10:11], v[100:101]
	v_pk_mul_f32 v[102:103], v[12:13], v[102:103]
	v_cvt_pk_bf16_f32 v28, v100, v101
	v_cvt_pk_bf16_f32 v29, v102, v103
	v_pk_mul_f32 v[104:105], v[104:105], v[62:63] op_sel_hi:[1,0]
	v_pk_mul_f32 v[106:107], v[106:107], v[62:63] op_sel_hi:[1,0]
	v_pk_mul_f32 v[104:105], v[6:7], v[104:105]
	v_pk_mul_f32 v[106:107], v[8:9], v[106:107]
	v_cvt_pk_bf16_f32 v30, v104, v105
	v_cvt_pk_bf16_f32 v31, v106, v107
	v_pk_mul_f32 v[108:109], v[108:109], v[62:63] op_sel_hi:[1,0]
	v_pk_mul_f32 v[110:111], v[110:111], v[62:63] op_sel_hi:[1,0]
	v_pk_mul_f32 v[108:109], v[2:3], v[108:109]
	v_pk_mul_f32 v[110:111], v[4:5], v[110:111]
	v_cvt_pk_bf16_f32 v32, v108, v109
	v_cvt_pk_bf16_f32 v33, v110, v111
	global_load_dwordx4 v[80:83], v34, s[0:1]
	global_load_dwordx4 v[84:87], v34, s[0:1] offset:1024
	global_load_dwordx4 v[88:91], v34, s[0:1] offset:2048
	global_load_dwordx4 v[92:95], v34, s[0:1] offset:3072
	s_add_u32 s0, s0, 0x800000
	s_addc_u32 s1, s1, 0
	global_load_dwordx4 v[96:99], v34, s[0:1]
	global_load_dwordx4 v[100:103], v34, s[0:1] offset:1024
	global_load_dwordx4 v[104:107], v34, s[0:1] offset:2048
	global_load_dwordx4 v[108:111], v34, s[0:1] offset:3072
	s_add_u32 s0, s0, 0x800000
	s_addc_u32 s1, s1, 0
	global_store_dwordx2 v46, v[18:19], s[2:3]
	global_store_dwordx2 v46, v[20:21], s[2:3] offset:512
	global_store_dwordx2 v46, v[22:23], s[2:3] offset:1024
	global_store_dwordx2 v46, v[24:25], s[2:3] offset:1536
	s_add_u32 s2, s2, 0x400000
	s_addc_u32 s3, s3, 0
	global_store_dwordx2 v46, v[26:27], s[2:3]
	global_store_dwordx2 v46, v[28:29], s[2:3] offset:512
	global_store_dwordx2 v46, v[30:31], s[2:3] offset:1024
	global_store_dwordx2 v46, v[32:33], s[2:3] offset:1536
	s_add_u32 s2, s2, 0x400000
	s_addc_u32 s3, s3, 0
	s_waitcnt vmcnt(16)
	v_pk_mul_f32 v[60:61], v[208:209], v[208:209]
	v_pk_mul_f32 v[62:63], v[210:211], v[210:211]
	v_pk_mul_f32 v[68:69], v[224:225], v[224:225]
	v_pk_mul_f32 v[70:71], v[226:227], v[226:227]
	v_pk_fma_f32 v[60:61], v[212:213], v[212:213], v[60:61]
	v_pk_fma_f32 v[62:63], v[214:215], v[214:215], v[62:63]
	v_pk_fma_f32 v[68:69], v[228:229], v[228:229], v[68:69]
	v_pk_fma_f32 v[70:71], v[230:231], v[230:231], v[70:71]
	v_pk_fma_f32 v[60:61], v[216:217], v[216:217], v[60:61]
	v_pk_fma_f32 v[62:63], v[218:219], v[218:219], v[62:63]
	v_pk_fma_f32 v[68:69], v[232:233], v[232:233], v[68:69]
	v_pk_fma_f32 v[70:71], v[234:235], v[234:235], v[70:71]
	v_pk_fma_f32 v[60:61], v[220:221], v[220:221], v[60:61]
	v_pk_fma_f32 v[62:63], v[222:223], v[222:223], v[62:63]
	v_pk_fma_f32 v[68:69], v[236:237], v[236:237], v[68:69]
	v_pk_fma_f32 v[70:71], v[238:239], v[238:239], v[70:71]
	v_pk_add_f32 v[60:61], v[60:61], v[62:63]
	v_pk_add_f32 v[68:69], v[68:69], v[70:71]
	v_add_f32_e32 v60, v60, v61
	v_add_f32_e32 v61, v68, v69
	ds_bpermute_b32 v62, v35, v60
	ds_bpermute_b32 v63, v35, v61
	s_waitcnt lgkmcnt(0)
	v_pk_add_f32 v[60:61], v[60:61], v[62:63]
	ds_bpermute_b32 v62, v36, v60
	ds_bpermute_b32 v63, v36, v61
	s_waitcnt lgkmcnt(0)
	v_pk_add_f32 v[60:61], v[60:61], v[62:63]
	ds_bpermute_b32 v62, v37, v60
	ds_bpermute_b32 v63, v37, v61
	s_waitcnt lgkmcnt(0)
	v_pk_add_f32 v[60:61], v[60:61], v[62:63]
	ds_bpermute_b32 v62, v38, v60
	ds_bpermute_b32 v63, v38, v61
	s_waitcnt lgkmcnt(0)
	v_pk_add_f32 v[60:61], v[60:61], v[62:63]
	ds_bpermute_b32 v62, v39, v60
	ds_bpermute_b32 v63, v39, v61
	s_waitcnt lgkmcnt(0)
	v_pk_add_f32 v[60:61], v[60:61], v[62:63]
	ds_bpermute_b32 v62, v40, v60
	ds_bpermute_b32 v63, v40, v61
	s_waitcnt lgkmcnt(0)
	v_pk_add_f32 v[60:61], v[60:61], v[62:63]
	v_fma_f32 v60, v60, s10, v52
	v_fma_f32 v62, v61, s10, v52
	v_rsq_f32_e32 v60, v60
	v_rsq_f32_e32 v62, v62
	s_nop 0
	v_pk_mul_f32 v[208:209], v[208:209], v[60:61] op_sel_hi:[1,0]
	v_pk_mul_f32 v[210:211], v[210:211], v[60:61] op_sel_hi:[1,0]
	v_pk_mul_f32 v[208:209], v[14:15], v[208:209]
	v_pk_mul_f32 v[210:211], v[16:17], v[210:211]
	v_cvt_pk_bf16_f32 v18, v208, v209
	v_cvt_pk_bf16_f32 v19, v210, v211
	v_pk_mul_f32 v[212:213], v[212:213], v[60:61] op_sel_hi:[1,0]
	v_pk_mul_f32 v[214:215], v[214:215], v[60:61] op_sel_hi:[1,0]
	v_pk_mul_f32 v[212:213], v[10:11], v[212:213]
	v_pk_mul_f32 v[214:215], v[12:13], v[214:215]
	v_cvt_pk_bf16_f32 v20, v212, v213
	v_cvt_pk_bf16_f32 v21, v214, v215
	v_pk_mul_f32 v[216:217], v[216:217], v[60:61] op_sel_hi:[1,0]
	v_pk_mul_f32 v[218:219], v[218:219], v[60:61] op_sel_hi:[1,0]
	v_pk_mul_f32 v[216:217], v[6:7], v[216:217]
	v_pk_mul_f32 v[218:219], v[8:9], v[218:219]
	v_cvt_pk_bf16_f32 v22, v216, v217
	v_cvt_pk_bf16_f32 v23, v218, v219
	v_pk_mul_f32 v[220:221], v[220:221], v[60:61] op_sel_hi:[1,0]
	v_pk_mul_f32 v[222:223], v[222:223], v[60:61] op_sel_hi:[1,0]
	v_pk_mul_f32 v[220:221], v[2:3], v[220:221]
	v_pk_mul_f32 v[222:223], v[4:5], v[222:223]
	v_cvt_pk_bf16_f32 v24, v220, v221
	v_cvt_pk_bf16_f32 v25, v222, v223
	v_pk_mul_f32 v[224:225], v[224:225], v[62:63] op_sel_hi:[1,0]
	v_pk_mul_f32 v[226:227], v[226:227], v[62:63] op_sel_hi:[1,0]
	v_pk_mul_f32 v[224:225], v[14:15], v[224:225]
	v_pk_mul_f32 v[226:227], v[16:17], v[226:227]
	v_cvt_pk_bf16_f32 v26, v224, v225
	v_cvt_pk_bf16_f32 v27, v226, v227
	v_pk_mul_f32 v[228:229], v[228:229], v[62:63] op_sel_hi:[1,0]
	v_pk_mul_f32 v[230:231], v[230:231], v[62:63] op_sel_hi:[1,0]
	v_pk_mul_f32 v[228:229], v[10:11], v[228:229]
	v_pk_mul_f32 v[230:231], v[12:13], v[230:231]
	v_cvt_pk_bf16_f32 v28, v228, v229
	v_cvt_pk_bf16_f32 v29, v230, v231
	v_pk_mul_f32 v[232:233], v[232:233], v[62:63] op_sel_hi:[1,0]
	v_pk_mul_f32 v[234:235], v[234:235], v[62:63] op_sel_hi:[1,0]
	v_pk_mul_f32 v[232:233], v[6:7], v[232:233]
	v_pk_mul_f32 v[234:235], v[8:9], v[234:235]
	v_cvt_pk_bf16_f32 v30, v232, v233
	v_cvt_pk_bf16_f32 v31, v234, v235
	v_pk_mul_f32 v[236:237], v[236:237], v[62:63] op_sel_hi:[1,0]
	v_pk_mul_f32 v[238:239], v[238:239], v[62:63] op_sel_hi:[1,0]
	v_pk_mul_f32 v[236:237], v[2:3], v[236:237]
	v_pk_mul_f32 v[238:239], v[4:5], v[238:239]
	v_cvt_pk_bf16_f32 v32, v236, v237
	v_cvt_pk_bf16_f32 v33, v238, v239
	global_load_dwordx4 v[208:211], v34, s[0:1]
	global_load_dwordx4 v[212:215], v34, s[0:1] offset:1024
	global_load_dwordx4 v[216:219], v34, s[0:1] offset:2048
	global_load_dwordx4 v[220:223], v34, s[0:1] offset:3072
	s_add_u32 s0, s0, 0x800000
	s_addc_u32 s1, s1, 0
	global_load_dwordx4 v[224:227], v34, s[0:1]
	global_load_dwordx4 v[228:231], v34, s[0:1] offset:1024
	global_load_dwordx4 v[232:235], v34, s[0:1] offset:2048
	global_load_dwordx4 v[236:239], v34, s[0:1] offset:3072
	s_add_u32 s0, s0, 0x800000
	s_addc_u32 s1, s1, 0
	global_store_dwordx2 v46, v[18:19], s[2:3]
	global_store_dwordx2 v46, v[20:21], s[2:3] offset:512
	global_store_dwordx2 v46, v[22:23], s[2:3] offset:1024
	global_store_dwordx2 v46, v[24:25], s[2:3] offset:1536
	s_add_u32 s2, s2, 0x400000
	s_addc_u32 s3, s3, 0
	global_store_dwordx2 v46, v[26:27], s[2:3]
	global_store_dwordx2 v46, v[28:29], s[2:3] offset:512
	global_store_dwordx2 v46, v[30:31], s[2:3] offset:1024
	global_store_dwordx2 v46, v[32:33], s[2:3] offset:1536
	s_add_u32 s2, s2, 0x400000
	s_addc_u32 s3, s3, 0
	s_waitcnt vmcnt(24)
	v_pk_mul_f32 v[60:61], v[80:81], v[80:81]
	v_pk_mul_f32 v[62:63], v[82:83], v[82:83]
	v_pk_mul_f32 v[68:69], v[96:97], v[96:97]
	v_pk_mul_f32 v[70:71], v[98:99], v[98:99]
	v_pk_fma_f32 v[60:61], v[84:85], v[84:85], v[60:61]
	v_pk_fma_f32 v[62:63], v[86:87], v[86:87], v[62:63]
	v_pk_fma_f32 v[68:69], v[100:101], v[100:101], v[68:69]
	v_pk_fma_f32 v[70:71], v[102:103], v[102:103], v[70:71]
	v_pk_fma_f32 v[60:61], v[88:89], v[88:89], v[60:61]
	v_pk_fma_f32 v[62:63], v[90:91], v[90:91], v[62:63]
	v_pk_fma_f32 v[68:69], v[104:105], v[104:105], v[68:69]
	v_pk_fma_f32 v[70:71], v[106:107], v[106:107], v[70:71]
	v_pk_fma_f32 v[60:61], v[92:93], v[92:93], v[60:61]
	v_pk_fma_f32 v[62:63], v[94:95], v[94:95], v[62:63]
	v_pk_fma_f32 v[68:69], v[108:109], v[108:109], v[68:69]
	v_pk_fma_f32 v[70:71], v[110:111], v[110:111], v[70:71]
	v_pk_add_f32 v[60:61], v[60:61], v[62:63]
	v_pk_add_f32 v[68:69], v[68:69], v[70:71]
	v_add_f32_e32 v60, v60, v61
	v_add_f32_e32 v61, v68, v69
	ds_bpermute_b32 v62, v35, v60
	ds_bpermute_b32 v63, v35, v61
	s_waitcnt lgkmcnt(0)
	v_pk_add_f32 v[60:61], v[60:61], v[62:63]
	ds_bpermute_b32 v62, v36, v60
	ds_bpermute_b32 v63, v36, v61
	s_waitcnt lgkmcnt(0)
	v_pk_add_f32 v[60:61], v[60:61], v[62:63]
	ds_bpermute_b32 v62, v37, v60
	ds_bpermute_b32 v63, v37, v61
	s_waitcnt lgkmcnt(0)
	v_pk_add_f32 v[60:61], v[60:61], v[62:63]
	ds_bpermute_b32 v62, v38, v60
	ds_bpermute_b32 v63, v38, v61
	s_waitcnt lgkmcnt(0)
	v_pk_add_f32 v[60:61], v[60:61], v[62:63]
	ds_bpermute_b32 v62, v39, v60
	ds_bpermute_b32 v63, v39, v61
	s_waitcnt lgkmcnt(0)
	v_pk_add_f32 v[60:61], v[60:61], v[62:63]
	ds_bpermute_b32 v62, v40, v60
	ds_bpermute_b32 v63, v40, v61
	s_waitcnt lgkmcnt(0)
	v_pk_add_f32 v[60:61], v[60:61], v[62:63]
	v_fma_f32 v60, v60, s10, v52
	v_fma_f32 v62, v61, s10, v52
	v_rsq_f32_e32 v60, v60
	v_rsq_f32_e32 v62, v62
	s_nop 0
	v_pk_mul_f32 v[80:81], v[80:81], v[60:61] op_sel_hi:[1,0]
	v_pk_mul_f32 v[82:83], v[82:83], v[60:61] op_sel_hi:[1,0]
	v_pk_mul_f32 v[80:81], v[14:15], v[80:81]
	v_pk_mul_f32 v[82:83], v[16:17], v[82:83]
	v_cvt_pk_bf16_f32 v18, v80, v81
	v_cvt_pk_bf16_f32 v19, v82, v83
	v_pk_mul_f32 v[84:85], v[84:85], v[60:61] op_sel_hi:[1,0]
	v_pk_mul_f32 v[86:87], v[86:87], v[60:61] op_sel_hi:[1,0]
	v_pk_mul_f32 v[84:85], v[10:11], v[84:85]
	v_pk_mul_f32 v[86:87], v[12:13], v[86:87]
	v_cvt_pk_bf16_f32 v20, v84, v85
	v_cvt_pk_bf16_f32 v21, v86, v87
	v_pk_mul_f32 v[88:89], v[88:89], v[60:61] op_sel_hi:[1,0]
	v_pk_mul_f32 v[90:91], v[90:91], v[60:61] op_sel_hi:[1,0]
	v_pk_mul_f32 v[88:89], v[6:7], v[88:89]
	v_pk_mul_f32 v[90:91], v[8:9], v[90:91]
	v_cvt_pk_bf16_f32 v22, v88, v89
	v_cvt_pk_bf16_f32 v23, v90, v91
	v_pk_mul_f32 v[92:93], v[92:93], v[60:61] op_sel_hi:[1,0]
	v_pk_mul_f32 v[94:95], v[94:95], v[60:61] op_sel_hi:[1,0]
	v_pk_mul_f32 v[92:93], v[2:3], v[92:93]
	v_pk_mul_f32 v[94:95], v[4:5], v[94:95]
	v_cvt_pk_bf16_f32 v24, v92, v93
	v_cvt_pk_bf16_f32 v25, v94, v95
	v_pk_mul_f32 v[96:97], v[96:97], v[62:63] op_sel_hi:[1,0]
	v_pk_mul_f32 v[98:99], v[98:99], v[62:63] op_sel_hi:[1,0]
	v_pk_mul_f32 v[96:97], v[14:15], v[96:97]
	v_pk_mul_f32 v[98:99], v[16:17], v[98:99]
	v_cvt_pk_bf16_f32 v26, v96, v97
	v_cvt_pk_bf16_f32 v27, v98, v99
	v_pk_mul_f32 v[100:101], v[100:101], v[62:63] op_sel_hi:[1,0]
	v_pk_mul_f32 v[102:103], v[102:103], v[62:63] op_sel_hi:[1,0]
	v_pk_mul_f32 v[100:101], v[10:11], v[100:101]
	v_pk_mul_f32 v[102:103], v[12:13], v[102:103]
	v_cvt_pk_bf16_f32 v28, v100, v101
	v_cvt_pk_bf16_f32 v29, v102, v103
	v_pk_mul_f32 v[104:105], v[104:105], v[62:63] op_sel_hi:[1,0]
	v_pk_mul_f32 v[106:107], v[106:107], v[62:63] op_sel_hi:[1,0]
	v_pk_mul_f32 v[104:105], v[6:7], v[104:105]
	v_pk_mul_f32 v[106:107], v[8:9], v[106:107]
	v_cvt_pk_bf16_f32 v30, v104, v105
	v_cvt_pk_bf16_f32 v31, v106, v107
	v_pk_mul_f32 v[108:109], v[108:109], v[62:63] op_sel_hi:[1,0]
	v_pk_mul_f32 v[110:111], v[110:111], v[62:63] op_sel_hi:[1,0]
	v_pk_mul_f32 v[108:109], v[2:3], v[108:109]
	v_pk_mul_f32 v[110:111], v[4:5], v[110:111]
	v_cvt_pk_bf16_f32 v32, v108, v109
	v_cvt_pk_bf16_f32 v33, v110, v111
	global_load_dwordx4 v[80:83], v34, s[0:1]
	global_load_dwordx4 v[84:87], v34, s[0:1] offset:1024
	global_load_dwordx4 v[88:91], v34, s[0:1] offset:2048
	global_load_dwordx4 v[92:95], v34, s[0:1] offset:3072
	s_add_u32 s0, s0, 0x800000
	s_addc_u32 s1, s1, 0
	global_load_dwordx4 v[96:99], v34, s[0:1]
	global_load_dwordx4 v[100:103], v34, s[0:1] offset:1024
	global_load_dwordx4 v[104:107], v34, s[0:1] offset:2048
	global_load_dwordx4 v[108:111], v34, s[0:1] offset:3072
	s_add_u32 s0, s0, 0x800000
	s_addc_u32 s1, s1, 0
	global_store_dwordx2 v46, v[18:19], s[2:3]
	global_store_dwordx2 v46, v[20:21], s[2:3] offset:512
	global_store_dwordx2 v46, v[22:23], s[2:3] offset:1024
	global_store_dwordx2 v46, v[24:25], s[2:3] offset:1536
	s_add_u32 s2, s2, 0x400000
	s_addc_u32 s3, s3, 0
	global_store_dwordx2 v46, v[26:27], s[2:3]
	global_store_dwordx2 v46, v[28:29], s[2:3] offset:512
	global_store_dwordx2 v46, v[30:31], s[2:3] offset:1024
	global_store_dwordx2 v46, v[32:33], s[2:3] offset:1536
	s_add_u32 s2, s2, 0x400000
	s_addc_u32 s3, s3, 0
	s_waitcnt vmcnt(24)
	v_pk_mul_f32 v[60:61], v[208:209], v[208:209]
	v_pk_mul_f32 v[62:63], v[210:211], v[210:211]
	v_pk_mul_f32 v[68:69], v[224:225], v[224:225]
	v_pk_mul_f32 v[70:71], v[226:227], v[226:227]
	v_pk_fma_f32 v[60:61], v[212:213], v[212:213], v[60:61]
	v_pk_fma_f32 v[62:63], v[214:215], v[214:215], v[62:63]
	v_pk_fma_f32 v[68:69], v[228:229], v[228:229], v[68:69]
	v_pk_fma_f32 v[70:71], v[230:231], v[230:231], v[70:71]
	v_pk_fma_f32 v[60:61], v[216:217], v[216:217], v[60:61]
	v_pk_fma_f32 v[62:63], v[218:219], v[218:219], v[62:63]
	v_pk_fma_f32 v[68:69], v[232:233], v[232:233], v[68:69]
	v_pk_fma_f32 v[70:71], v[234:235], v[234:235], v[70:71]
	v_pk_fma_f32 v[60:61], v[220:221], v[220:221], v[60:61]
	v_pk_fma_f32 v[62:63], v[222:223], v[222:223], v[62:63]
	v_pk_fma_f32 v[68:69], v[236:237], v[236:237], v[68:69]
	v_pk_fma_f32 v[70:71], v[238:239], v[238:239], v[70:71]
	v_pk_add_f32 v[60:61], v[60:61], v[62:63]
	v_pk_add_f32 v[68:69], v[68:69], v[70:71]
	v_add_f32_e32 v60, v60, v61
	v_add_f32_e32 v61, v68, v69
	ds_bpermute_b32 v62, v35, v60
	ds_bpermute_b32 v63, v35, v61
	s_waitcnt lgkmcnt(0)
	v_pk_add_f32 v[60:61], v[60:61], v[62:63]
	ds_bpermute_b32 v62, v36, v60
	ds_bpermute_b32 v63, v36, v61
	s_waitcnt lgkmcnt(0)
	v_pk_add_f32 v[60:61], v[60:61], v[62:63]
	ds_bpermute_b32 v62, v37, v60
	ds_bpermute_b32 v63, v37, v61
	s_waitcnt lgkmcnt(0)
	v_pk_add_f32 v[60:61], v[60:61], v[62:63]
	ds_bpermute_b32 v62, v38, v60
	ds_bpermute_b32 v63, v38, v61
	s_waitcnt lgkmcnt(0)
	v_pk_add_f32 v[60:61], v[60:61], v[62:63]
	ds_bpermute_b32 v62, v39, v60
	ds_bpermute_b32 v63, v39, v61
	s_waitcnt lgkmcnt(0)
	v_pk_add_f32 v[60:61], v[60:61], v[62:63]
	ds_bpermute_b32 v62, v40, v60
	ds_bpermute_b32 v63, v40, v61
	s_waitcnt lgkmcnt(0)
	v_pk_add_f32 v[60:61], v[60:61], v[62:63]
	v_fma_f32 v60, v60, s10, v52
	v_fma_f32 v62, v61, s10, v52
	v_rsq_f32_e32 v60, v60
	v_rsq_f32_e32 v62, v62
	s_nop 0
	v_pk_mul_f32 v[208:209], v[208:209], v[60:61] op_sel_hi:[1,0]
	v_pk_mul_f32 v[210:211], v[210:211], v[60:61] op_sel_hi:[1,0]
	v_pk_mul_f32 v[208:209], v[14:15], v[208:209]
	v_pk_mul_f32 v[210:211], v[16:17], v[210:211]
	v_cvt_pk_bf16_f32 v18, v208, v209
	v_cvt_pk_bf16_f32 v19, v210, v211
	v_pk_mul_f32 v[212:213], v[212:213], v[60:61] op_sel_hi:[1,0]
	v_pk_mul_f32 v[214:215], v[214:215], v[60:61] op_sel_hi:[1,0]
	v_pk_mul_f32 v[212:213], v[10:11], v[212:213]
	v_pk_mul_f32 v[214:215], v[12:13], v[214:215]
	v_cvt_pk_bf16_f32 v20, v212, v213
	v_cvt_pk_bf16_f32 v21, v214, v215
	v_pk_mul_f32 v[216:217], v[216:217], v[60:61] op_sel_hi:[1,0]
	v_pk_mul_f32 v[218:219], v[218:219], v[60:61] op_sel_hi:[1,0]
	v_pk_mul_f32 v[216:217], v[6:7], v[216:217]
	v_pk_mul_f32 v[218:219], v[8:9], v[218:219]
	v_cvt_pk_bf16_f32 v22, v216, v217
	v_cvt_pk_bf16_f32 v23, v218, v219
	v_pk_mul_f32 v[220:221], v[220:221], v[60:61] op_sel_hi:[1,0]
	v_pk_mul_f32 v[222:223], v[222:223], v[60:61] op_sel_hi:[1,0]
	v_pk_mul_f32 v[220:221], v[2:3], v[220:221]
	v_pk_mul_f32 v[222:223], v[4:5], v[222:223]
	v_cvt_pk_bf16_f32 v24, v220, v221
	v_cvt_pk_bf16_f32 v25, v222, v223
	v_pk_mul_f32 v[224:225], v[224:225], v[62:63] op_sel_hi:[1,0]
	v_pk_mul_f32 v[226:227], v[226:227], v[62:63] op_sel_hi:[1,0]
	v_pk_mul_f32 v[224:225], v[14:15], v[224:225]
	v_pk_mul_f32 v[226:227], v[16:17], v[226:227]
	v_cvt_pk_bf16_f32 v26, v224, v225
	v_cvt_pk_bf16_f32 v27, v226, v227
	v_pk_mul_f32 v[228:229], v[228:229], v[62:63] op_sel_hi:[1,0]
	v_pk_mul_f32 v[230:231], v[230:231], v[62:63] op_sel_hi:[1,0]
	v_pk_mul_f32 v[228:229], v[10:11], v[228:229]
	v_pk_mul_f32 v[230:231], v[12:13], v[230:231]
	v_cvt_pk_bf16_f32 v28, v228, v229
	v_cvt_pk_bf16_f32 v29, v230, v231
	v_pk_mul_f32 v[232:233], v[232:233], v[62:63] op_sel_hi:[1,0]
	v_pk_mul_f32 v[234:235], v[234:235], v[62:63] op_sel_hi:[1,0]
	v_pk_mul_f32 v[232:233], v[6:7], v[232:233]
	v_pk_mul_f32 v[234:235], v[8:9], v[234:235]
	v_cvt_pk_bf16_f32 v30, v232, v233
	v_cvt_pk_bf16_f32 v31, v234, v235
	v_pk_mul_f32 v[236:237], v[236:237], v[62:63] op_sel_hi:[1,0]
	v_pk_mul_f32 v[238:239], v[238:239], v[62:63] op_sel_hi:[1,0]
	v_pk_mul_f32 v[236:237], v[2:3], v[236:237]
	v_pk_mul_f32 v[238:239], v[4:5], v[238:239]
	v_cvt_pk_bf16_f32 v32, v236, v237
	v_cvt_pk_bf16_f32 v33, v238, v239
	global_load_dwordx4 v[208:211], v34, s[0:1]
	global_load_dwordx4 v[212:215], v34, s[0:1] offset:1024
	global_load_dwordx4 v[216:219], v34, s[0:1] offset:2048
	global_load_dwordx4 v[220:223], v34, s[0:1] offset:3072
	s_add_u32 s0, s0, 0x800000
	s_addc_u32 s1, s1, 0
	global_load_dwordx4 v[224:227], v34, s[0:1]
	global_load_dwordx4 v[228:231], v34, s[0:1] offset:1024
	global_load_dwordx4 v[232:235], v34, s[0:1] offset:2048
	global_load_dwordx4 v[236:239], v34, s[0:1] offset:3072
	s_add_u32 s0, s0, 0x800000
	s_addc_u32 s1, s1, 0
	global_store_dwordx2 v46, v[18:19], s[2:3]
	global_store_dwordx2 v46, v[20:21], s[2:3] offset:512
	global_store_dwordx2 v46, v[22:23], s[2:3] offset:1024
	global_store_dwordx2 v46, v[24:25], s[2:3] offset:1536
	s_add_u32 s2, s2, 0x400000
	s_addc_u32 s3, s3, 0
	global_store_dwordx2 v46, v[26:27], s[2:3]
	global_store_dwordx2 v46, v[28:29], s[2:3] offset:512
	global_store_dwordx2 v46, v[30:31], s[2:3] offset:1024
	global_store_dwordx2 v46, v[32:33], s[2:3] offset:1536
	s_add_u32 s2, s2, 0x400000
	s_addc_u32 s3, s3, 0
	s_waitcnt vmcnt(24)
	v_pk_mul_f32 v[60:61], v[80:81], v[80:81]
	v_pk_mul_f32 v[62:63], v[82:83], v[82:83]
	v_pk_mul_f32 v[68:69], v[96:97], v[96:97]
	v_pk_mul_f32 v[70:71], v[98:99], v[98:99]
	v_pk_fma_f32 v[60:61], v[84:85], v[84:85], v[60:61]
	v_pk_fma_f32 v[62:63], v[86:87], v[86:87], v[62:63]
	v_pk_fma_f32 v[68:69], v[100:101], v[100:101], v[68:69]
	v_pk_fma_f32 v[70:71], v[102:103], v[102:103], v[70:71]
	v_pk_fma_f32 v[60:61], v[88:89], v[88:89], v[60:61]
	v_pk_fma_f32 v[62:63], v[90:91], v[90:91], v[62:63]
	v_pk_fma_f32 v[68:69], v[104:105], v[104:105], v[68:69]
	v_pk_fma_f32 v[70:71], v[106:107], v[106:107], v[70:71]
	v_pk_fma_f32 v[60:61], v[92:93], v[92:93], v[60:61]
	v_pk_fma_f32 v[62:63], v[94:95], v[94:95], v[62:63]
	v_pk_fma_f32 v[68:69], v[108:109], v[108:109], v[68:69]
	v_pk_fma_f32 v[70:71], v[110:111], v[110:111], v[70:71]
	v_pk_add_f32 v[60:61], v[60:61], v[62:63]
	v_pk_add_f32 v[68:69], v[68:69], v[70:71]
	v_add_f32_e32 v60, v60, v61
	v_add_f32_e32 v61, v68, v69
	ds_bpermute_b32 v62, v35, v60
	ds_bpermute_b32 v63, v35, v61
	s_waitcnt lgkmcnt(0)
	v_pk_add_f32 v[60:61], v[60:61], v[62:63]
	ds_bpermute_b32 v62, v36, v60
	ds_bpermute_b32 v63, v36, v61
	s_waitcnt lgkmcnt(0)
	v_pk_add_f32 v[60:61], v[60:61], v[62:63]
	ds_bpermute_b32 v62, v37, v60
	ds_bpermute_b32 v63, v37, v61
	s_waitcnt lgkmcnt(0)
	v_pk_add_f32 v[60:61], v[60:61], v[62:63]
	ds_bpermute_b32 v62, v38, v60
	ds_bpermute_b32 v63, v38, v61
	s_waitcnt lgkmcnt(0)
	v_pk_add_f32 v[60:61], v[60:61], v[62:63]
	ds_bpermute_b32 v62, v39, v60
	ds_bpermute_b32 v63, v39, v61
	s_waitcnt lgkmcnt(0)
	v_pk_add_f32 v[60:61], v[60:61], v[62:63]
	ds_bpermute_b32 v62, v40, v60
	ds_bpermute_b32 v63, v40, v61
	s_waitcnt lgkmcnt(0)
	v_pk_add_f32 v[60:61], v[60:61], v[62:63]
	v_fma_f32 v60, v60, s10, v52
	v_fma_f32 v62, v61, s10, v52
	v_rsq_f32_e32 v60, v60
	v_rsq_f32_e32 v62, v62
	s_nop 0
	v_pk_mul_f32 v[80:81], v[80:81], v[60:61] op_sel_hi:[1,0]
	v_pk_mul_f32 v[82:83], v[82:83], v[60:61] op_sel_hi:[1,0]
	v_pk_mul_f32 v[80:81], v[14:15], v[80:81]
	v_pk_mul_f32 v[82:83], v[16:17], v[82:83]
	v_cvt_pk_bf16_f32 v18, v80, v81
	v_cvt_pk_bf16_f32 v19, v82, v83
	v_pk_mul_f32 v[84:85], v[84:85], v[60:61] op_sel_hi:[1,0]
	v_pk_mul_f32 v[86:87], v[86:87], v[60:61] op_sel_hi:[1,0]
	v_pk_mul_f32 v[84:85], v[10:11], v[84:85]
	v_pk_mul_f32 v[86:87], v[12:13], v[86:87]
	v_cvt_pk_bf16_f32 v20, v84, v85
	v_cvt_pk_bf16_f32 v21, v86, v87
	v_pk_mul_f32 v[88:89], v[88:89], v[60:61] op_sel_hi:[1,0]
	v_pk_mul_f32 v[90:91], v[90:91], v[60:61] op_sel_hi:[1,0]
	v_pk_mul_f32 v[88:89], v[6:7], v[88:89]
	v_pk_mul_f32 v[90:91], v[8:9], v[90:91]
	v_cvt_pk_bf16_f32 v22, v88, v89
	v_cvt_pk_bf16_f32 v23, v90, v91
	v_pk_mul_f32 v[92:93], v[92:93], v[60:61] op_sel_hi:[1,0]
	v_pk_mul_f32 v[94:95], v[94:95], v[60:61] op_sel_hi:[1,0]
	v_pk_mul_f32 v[92:93], v[2:3], v[92:93]
	v_pk_mul_f32 v[94:95], v[4:5], v[94:95]
	v_cvt_pk_bf16_f32 v24, v92, v93
	v_cvt_pk_bf16_f32 v25, v94, v95
	v_pk_mul_f32 v[96:97], v[96:97], v[62:63] op_sel_hi:[1,0]
	v_pk_mul_f32 v[98:99], v[98:99], v[62:63] op_sel_hi:[1,0]
	v_pk_mul_f32 v[96:97], v[14:15], v[96:97]
	v_pk_mul_f32 v[98:99], v[16:17], v[98:99]
	v_cvt_pk_bf16_f32 v26, v96, v97
	v_cvt_pk_bf16_f32 v27, v98, v99
	v_pk_mul_f32 v[100:101], v[100:101], v[62:63] op_sel_hi:[1,0]
	v_pk_mul_f32 v[102:103], v[102:103], v[62:63] op_sel_hi:[1,0]
	v_pk_mul_f32 v[100:101], v[10:11], v[100:101]
	v_pk_mul_f32 v[102:103], v[12:13], v[102:103]
	v_cvt_pk_bf16_f32 v28, v100, v101
	v_cvt_pk_bf16_f32 v29, v102, v103
	v_pk_mul_f32 v[104:105], v[104:105], v[62:63] op_sel_hi:[1,0]
	v_pk_mul_f32 v[106:107], v[106:107], v[62:63] op_sel_hi:[1,0]
	v_pk_mul_f32 v[104:105], v[6:7], v[104:105]
	v_pk_mul_f32 v[106:107], v[8:9], v[106:107]
	v_cvt_pk_bf16_f32 v30, v104, v105
	v_cvt_pk_bf16_f32 v31, v106, v107
	v_pk_mul_f32 v[108:109], v[108:109], v[62:63] op_sel_hi:[1,0]
	v_pk_mul_f32 v[110:111], v[110:111], v[62:63] op_sel_hi:[1,0]
	v_pk_mul_f32 v[108:109], v[2:3], v[108:109]
	v_pk_mul_f32 v[110:111], v[4:5], v[110:111]
	v_cvt_pk_bf16_f32 v32, v108, v109
	v_cvt_pk_bf16_f32 v33, v110, v111
	global_load_dwordx4 v[80:83], v34, s[0:1]
	global_load_dwordx4 v[84:87], v34, s[0:1] offset:1024
	global_load_dwordx4 v[88:91], v34, s[0:1] offset:2048
	global_load_dwordx4 v[92:95], v34, s[0:1] offset:3072
	s_add_u32 s0, s0, 0x800000
	s_addc_u32 s1, s1, 0
	global_load_dwordx4 v[96:99], v34, s[0:1]
	global_load_dwordx4 v[100:103], v34, s[0:1] offset:1024
	global_load_dwordx4 v[104:107], v34, s[0:1] offset:2048
	global_load_dwordx4 v[108:111], v34, s[0:1] offset:3072
	s_add_u32 s0, s0, 0x800000
	s_addc_u32 s1, s1, 0
	global_store_dwordx2 v46, v[18:19], s[2:3]
	global_store_dwordx2 v46, v[20:21], s[2:3] offset:512
	global_store_dwordx2 v46, v[22:23], s[2:3] offset:1024
	global_store_dwordx2 v46, v[24:25], s[2:3] offset:1536
	s_add_u32 s2, s2, 0x400000
	s_addc_u32 s3, s3, 0
	global_store_dwordx2 v46, v[26:27], s[2:3]
	global_store_dwordx2 v46, v[28:29], s[2:3] offset:512
	global_store_dwordx2 v46, v[30:31], s[2:3] offset:1024
	global_store_dwordx2 v46, v[32:33], s[2:3] offset:1536
	s_add_u32 s2, s2, 0x400000
	s_addc_u32 s3, s3, 0
	s_waitcnt vmcnt(24)
	v_pk_mul_f32 v[60:61], v[208:209], v[208:209]
	v_pk_mul_f32 v[62:63], v[210:211], v[210:211]
	v_pk_mul_f32 v[68:69], v[224:225], v[224:225]
	v_pk_mul_f32 v[70:71], v[226:227], v[226:227]
	v_pk_fma_f32 v[60:61], v[212:213], v[212:213], v[60:61]
	v_pk_fma_f32 v[62:63], v[214:215], v[214:215], v[62:63]
	v_pk_fma_f32 v[68:69], v[228:229], v[228:229], v[68:69]
	v_pk_fma_f32 v[70:71], v[230:231], v[230:231], v[70:71]
	v_pk_fma_f32 v[60:61], v[216:217], v[216:217], v[60:61]
	v_pk_fma_f32 v[62:63], v[218:219], v[218:219], v[62:63]
	v_pk_fma_f32 v[68:69], v[232:233], v[232:233], v[68:69]
	v_pk_fma_f32 v[70:71], v[234:235], v[234:235], v[70:71]
	v_pk_fma_f32 v[60:61], v[220:221], v[220:221], v[60:61]
	v_pk_fma_f32 v[62:63], v[222:223], v[222:223], v[62:63]
	v_pk_fma_f32 v[68:69], v[236:237], v[236:237], v[68:69]
	v_pk_fma_f32 v[70:71], v[238:239], v[238:239], v[70:71]
	v_pk_add_f32 v[60:61], v[60:61], v[62:63]
	v_pk_add_f32 v[68:69], v[68:69], v[70:71]
	v_add_f32_e32 v60, v60, v61
	v_add_f32_e32 v61, v68, v69
	ds_bpermute_b32 v62, v35, v60
	ds_bpermute_b32 v63, v35, v61
	s_waitcnt lgkmcnt(0)
	v_pk_add_f32 v[60:61], v[60:61], v[62:63]
	ds_bpermute_b32 v62, v36, v60
	ds_bpermute_b32 v63, v36, v61
	s_waitcnt lgkmcnt(0)
	v_pk_add_f32 v[60:61], v[60:61], v[62:63]
	ds_bpermute_b32 v62, v37, v60
	ds_bpermute_b32 v63, v37, v61
	s_waitcnt lgkmcnt(0)
	v_pk_add_f32 v[60:61], v[60:61], v[62:63]
	ds_bpermute_b32 v62, v38, v60
	ds_bpermute_b32 v63, v38, v61
	s_waitcnt lgkmcnt(0)
	v_pk_add_f32 v[60:61], v[60:61], v[62:63]
	ds_bpermute_b32 v62, v39, v60
	ds_bpermute_b32 v63, v39, v61
	s_waitcnt lgkmcnt(0)
	v_pk_add_f32 v[60:61], v[60:61], v[62:63]
	ds_bpermute_b32 v62, v40, v60
	ds_bpermute_b32 v63, v40, v61
	s_waitcnt lgkmcnt(0)
	v_pk_add_f32 v[60:61], v[60:61], v[62:63]
	v_fma_f32 v60, v60, s10, v52
	v_fma_f32 v62, v61, s10, v52
	v_rsq_f32_e32 v60, v60
	v_rsq_f32_e32 v62, v62
	s_nop 0
	v_pk_mul_f32 v[208:209], v[208:209], v[60:61] op_sel_hi:[1,0]
	v_pk_mul_f32 v[210:211], v[210:211], v[60:61] op_sel_hi:[1,0]
	v_pk_mul_f32 v[208:209], v[14:15], v[208:209]
	v_pk_mul_f32 v[210:211], v[16:17], v[210:211]
	v_cvt_pk_bf16_f32 v18, v208, v209
	v_cvt_pk_bf16_f32 v19, v210, v211
	v_pk_mul_f32 v[212:213], v[212:213], v[60:61] op_sel_hi:[1,0]
	v_pk_mul_f32 v[214:215], v[214:215], v[60:61] op_sel_hi:[1,0]
	v_pk_mul_f32 v[212:213], v[10:11], v[212:213]
	v_pk_mul_f32 v[214:215], v[12:13], v[214:215]
	v_cvt_pk_bf16_f32 v20, v212, v213
	v_cvt_pk_bf16_f32 v21, v214, v215
	v_pk_mul_f32 v[216:217], v[216:217], v[60:61] op_sel_hi:[1,0]
	v_pk_mul_f32 v[218:219], v[218:219], v[60:61] op_sel_hi:[1,0]
	v_pk_mul_f32 v[216:217], v[6:7], v[216:217]
	v_pk_mul_f32 v[218:219], v[8:9], v[218:219]
	v_cvt_pk_bf16_f32 v22, v216, v217
	v_cvt_pk_bf16_f32 v23, v218, v219
	v_pk_mul_f32 v[220:221], v[220:221], v[60:61] op_sel_hi:[1,0]
	v_pk_mul_f32 v[222:223], v[222:223], v[60:61] op_sel_hi:[1,0]
	v_pk_mul_f32 v[220:221], v[2:3], v[220:221]
	v_pk_mul_f32 v[222:223], v[4:5], v[222:223]
	v_cvt_pk_bf16_f32 v24, v220, v221
	v_cvt_pk_bf16_f32 v25, v222, v223
	v_pk_mul_f32 v[224:225], v[224:225], v[62:63] op_sel_hi:[1,0]
	v_pk_mul_f32 v[226:227], v[226:227], v[62:63] op_sel_hi:[1,0]
	v_pk_mul_f32 v[224:225], v[14:15], v[224:225]
	v_pk_mul_f32 v[226:227], v[16:17], v[226:227]
	v_cvt_pk_bf16_f32 v26, v224, v225
	v_cvt_pk_bf16_f32 v27, v226, v227
	v_pk_mul_f32 v[228:229], v[228:229], v[62:63] op_sel_hi:[1,0]
	v_pk_mul_f32 v[230:231], v[230:231], v[62:63] op_sel_hi:[1,0]
	v_pk_mul_f32 v[228:229], v[10:11], v[228:229]
	v_pk_mul_f32 v[230:231], v[12:13], v[230:231]
	v_cvt_pk_bf16_f32 v28, v228, v229
	v_cvt_pk_bf16_f32 v29, v230, v231
	v_pk_mul_f32 v[232:233], v[232:233], v[62:63] op_sel_hi:[1,0]
	v_pk_mul_f32 v[234:235], v[234:235], v[62:63] op_sel_hi:[1,0]
	v_pk_mul_f32 v[232:233], v[6:7], v[232:233]
	v_pk_mul_f32 v[234:235], v[8:9], v[234:235]
	v_cvt_pk_bf16_f32 v30, v232, v233
	v_cvt_pk_bf16_f32 v31, v234, v235
	v_pk_mul_f32 v[236:237], v[236:237], v[62:63] op_sel_hi:[1,0]
	v_pk_mul_f32 v[238:239], v[238:239], v[62:63] op_sel_hi:[1,0]
	v_pk_mul_f32 v[236:237], v[2:3], v[236:237]
	v_pk_mul_f32 v[238:239], v[4:5], v[238:239]
	v_cvt_pk_bf16_f32 v32, v236, v237
	v_cvt_pk_bf16_f32 v33, v238, v239
	global_load_dwordx4 v[208:211], v34, s[0:1]
	global_load_dwordx4 v[212:215], v34, s[0:1] offset:1024
	global_load_dwordx4 v[216:219], v34, s[0:1] offset:2048
	global_load_dwordx4 v[220:223], v34, s[0:1] offset:3072
	s_add_u32 s0, s0, 0x800000
	s_addc_u32 s1, s1, 0
	global_load_dwordx4 v[224:227], v34, s[0:1]
	global_load_dwordx4 v[228:231], v34, s[0:1] offset:1024
	global_load_dwordx4 v[232:235], v34, s[0:1] offset:2048
	global_load_dwordx4 v[236:239], v34, s[0:1] offset:3072
	s_add_u32 s0, s0, 0x800000
	s_addc_u32 s1, s1, 0
	global_store_dwordx2 v46, v[18:19], s[2:3]
	global_store_dwordx2 v46, v[20:21], s[2:3] offset:512
	global_store_dwordx2 v46, v[22:23], s[2:3] offset:1024
	global_store_dwordx2 v46, v[24:25], s[2:3] offset:1536
	s_add_u32 s2, s2, 0x400000
	s_addc_u32 s3, s3, 0
	global_store_dwordx2 v46, v[26:27], s[2:3]
	global_store_dwordx2 v46, v[28:29], s[2:3] offset:512
	global_store_dwordx2 v46, v[30:31], s[2:3] offset:1024
	global_store_dwordx2 v46, v[32:33], s[2:3] offset:1536
	s_add_u32 s2, s2, 0x400000
	s_addc_u32 s3, s3, 0
	s_waitcnt vmcnt(24)
	v_pk_mul_f32 v[60:61], v[80:81], v[80:81]
	v_pk_mul_f32 v[62:63], v[82:83], v[82:83]
	v_pk_mul_f32 v[68:69], v[96:97], v[96:97]
	v_pk_mul_f32 v[70:71], v[98:99], v[98:99]
	v_pk_fma_f32 v[60:61], v[84:85], v[84:85], v[60:61]
	v_pk_fma_f32 v[62:63], v[86:87], v[86:87], v[62:63]
	v_pk_fma_f32 v[68:69], v[100:101], v[100:101], v[68:69]
	v_pk_fma_f32 v[70:71], v[102:103], v[102:103], v[70:71]
	v_pk_fma_f32 v[60:61], v[88:89], v[88:89], v[60:61]
	v_pk_fma_f32 v[62:63], v[90:91], v[90:91], v[62:63]
	v_pk_fma_f32 v[68:69], v[104:105], v[104:105], v[68:69]
	v_pk_fma_f32 v[70:71], v[106:107], v[106:107], v[70:71]
	v_pk_fma_f32 v[60:61], v[92:93], v[92:93], v[60:61]
	v_pk_fma_f32 v[62:63], v[94:95], v[94:95], v[62:63]
	v_pk_fma_f32 v[68:69], v[108:109], v[108:109], v[68:69]
	v_pk_fma_f32 v[70:71], v[110:111], v[110:111], v[70:71]
	v_pk_add_f32 v[60:61], v[60:61], v[62:63]
	v_pk_add_f32 v[68:69], v[68:69], v[70:71]
	v_add_f32_e32 v60, v60, v61
	v_add_f32_e32 v61, v68, v69
	ds_bpermute_b32 v62, v35, v60
	ds_bpermute_b32 v63, v35, v61
	s_waitcnt lgkmcnt(0)
	v_pk_add_f32 v[60:61], v[60:61], v[62:63]
	ds_bpermute_b32 v62, v36, v60
	ds_bpermute_b32 v63, v36, v61
	s_waitcnt lgkmcnt(0)
	v_pk_add_f32 v[60:61], v[60:61], v[62:63]
	ds_bpermute_b32 v62, v37, v60
	ds_bpermute_b32 v63, v37, v61
	s_waitcnt lgkmcnt(0)
	v_pk_add_f32 v[60:61], v[60:61], v[62:63]
	ds_bpermute_b32 v62, v38, v60
	ds_bpermute_b32 v63, v38, v61
	s_waitcnt lgkmcnt(0)
	v_pk_add_f32 v[60:61], v[60:61], v[62:63]
	ds_bpermute_b32 v62, v39, v60
	ds_bpermute_b32 v63, v39, v61
	s_waitcnt lgkmcnt(0)
	v_pk_add_f32 v[60:61], v[60:61], v[62:63]
	ds_bpermute_b32 v62, v40, v60
	ds_bpermute_b32 v63, v40, v61
	s_waitcnt lgkmcnt(0)
	v_pk_add_f32 v[60:61], v[60:61], v[62:63]
	v_fma_f32 v60, v60, s10, v52
	v_fma_f32 v62, v61, s10, v52
	v_rsq_f32_e32 v60, v60
	v_rsq_f32_e32 v62, v62
	s_nop 0
	v_pk_mul_f32 v[80:81], v[80:81], v[60:61] op_sel_hi:[1,0]
	v_pk_mul_f32 v[82:83], v[82:83], v[60:61] op_sel_hi:[1,0]
	v_pk_mul_f32 v[80:81], v[14:15], v[80:81]
	v_pk_mul_f32 v[82:83], v[16:17], v[82:83]
	v_cvt_pk_bf16_f32 v18, v80, v81
	v_cvt_pk_bf16_f32 v19, v82, v83
	v_pk_mul_f32 v[84:85], v[84:85], v[60:61] op_sel_hi:[1,0]
	v_pk_mul_f32 v[86:87], v[86:87], v[60:61] op_sel_hi:[1,0]
	v_pk_mul_f32 v[84:85], v[10:11], v[84:85]
	v_pk_mul_f32 v[86:87], v[12:13], v[86:87]
	v_cvt_pk_bf16_f32 v20, v84, v85
	v_cvt_pk_bf16_f32 v21, v86, v87
	v_pk_mul_f32 v[88:89], v[88:89], v[60:61] op_sel_hi:[1,0]
	v_pk_mul_f32 v[90:91], v[90:91], v[60:61] op_sel_hi:[1,0]
	v_pk_mul_f32 v[88:89], v[6:7], v[88:89]
	v_pk_mul_f32 v[90:91], v[8:9], v[90:91]
	v_cvt_pk_bf16_f32 v22, v88, v89
	v_cvt_pk_bf16_f32 v23, v90, v91
	v_pk_mul_f32 v[92:93], v[92:93], v[60:61] op_sel_hi:[1,0]
	v_pk_mul_f32 v[94:95], v[94:95], v[60:61] op_sel_hi:[1,0]
	v_pk_mul_f32 v[92:93], v[2:3], v[92:93]
	v_pk_mul_f32 v[94:95], v[4:5], v[94:95]
	v_cvt_pk_bf16_f32 v24, v92, v93
	v_cvt_pk_bf16_f32 v25, v94, v95
	v_pk_mul_f32 v[96:97], v[96:97], v[62:63] op_sel_hi:[1,0]
	v_pk_mul_f32 v[98:99], v[98:99], v[62:63] op_sel_hi:[1,0]
	v_pk_mul_f32 v[96:97], v[14:15], v[96:97]
	v_pk_mul_f32 v[98:99], v[16:17], v[98:99]
	v_cvt_pk_bf16_f32 v26, v96, v97
	v_cvt_pk_bf16_f32 v27, v98, v99
	v_pk_mul_f32 v[100:101], v[100:101], v[62:63] op_sel_hi:[1,0]
	v_pk_mul_f32 v[102:103], v[102:103], v[62:63] op_sel_hi:[1,0]
	v_pk_mul_f32 v[100:101], v[10:11], v[100:101]
	v_pk_mul_f32 v[102:103], v[12:13], v[102:103]
	v_cvt_pk_bf16_f32 v28, v100, v101
	v_cvt_pk_bf16_f32 v29, v102, v103
	v_pk_mul_f32 v[104:105], v[104:105], v[62:63] op_sel_hi:[1,0]
	v_pk_mul_f32 v[106:107], v[106:107], v[62:63] op_sel_hi:[1,0]
	v_pk_mul_f32 v[104:105], v[6:7], v[104:105]
	v_pk_mul_f32 v[106:107], v[8:9], v[106:107]
	v_cvt_pk_bf16_f32 v30, v104, v105
	v_cvt_pk_bf16_f32 v31, v106, v107
	v_pk_mul_f32 v[108:109], v[108:109], v[62:63] op_sel_hi:[1,0]
	v_pk_mul_f32 v[110:111], v[110:111], v[62:63] op_sel_hi:[1,0]
	v_pk_mul_f32 v[108:109], v[2:3], v[108:109]
	v_pk_mul_f32 v[110:111], v[4:5], v[110:111]
	v_cvt_pk_bf16_f32 v32, v108, v109
	v_cvt_pk_bf16_f32 v33, v110, v111
	global_store_dwordx2 v46, v[18:19], s[2:3]
	global_store_dwordx2 v46, v[20:21], s[2:3] offset:512
	global_store_dwordx2 v46, v[22:23], s[2:3] offset:1024
	global_store_dwordx2 v46, v[24:25], s[2:3] offset:1536
	s_add_u32 s2, s2, 0x400000
	s_addc_u32 s3, s3, 0
	global_store_dwordx2 v46, v[26:27], s[2:3]
	global_store_dwordx2 v46, v[28:29], s[2:3] offset:512
	global_store_dwordx2 v46, v[30:31], s[2:3] offset:1024
	global_store_dwordx2 v46, v[32:33], s[2:3] offset:1536
	s_add_u32 s2, s2, 0x400000
	s_addc_u32 s3, s3, 0
	s_waitcnt vmcnt(16)
	v_pk_mul_f32 v[60:61], v[208:209], v[208:209]
	v_pk_mul_f32 v[62:63], v[210:211], v[210:211]
	v_pk_mul_f32 v[68:69], v[224:225], v[224:225]
	v_pk_mul_f32 v[70:71], v[226:227], v[226:227]
	v_pk_fma_f32 v[60:61], v[212:213], v[212:213], v[60:61]
	v_pk_fma_f32 v[62:63], v[214:215], v[214:215], v[62:63]
	v_pk_fma_f32 v[68:69], v[228:229], v[228:229], v[68:69]
	v_pk_fma_f32 v[70:71], v[230:231], v[230:231], v[70:71]
	v_pk_fma_f32 v[60:61], v[216:217], v[216:217], v[60:61]
	v_pk_fma_f32 v[62:63], v[218:219], v[218:219], v[62:63]
	v_pk_fma_f32 v[68:69], v[232:233], v[232:233], v[68:69]
	v_pk_fma_f32 v[70:71], v[234:235], v[234:235], v[70:71]
	v_pk_fma_f32 v[60:61], v[220:221], v[220:221], v[60:61]
	v_pk_fma_f32 v[62:63], v[222:223], v[222:223], v[62:63]
	v_pk_fma_f32 v[68:69], v[236:237], v[236:237], v[68:69]
	v_pk_fma_f32 v[70:71], v[238:239], v[238:239], v[70:71]
	v_pk_add_f32 v[60:61], v[60:61], v[62:63]
	v_pk_add_f32 v[68:69], v[68:69], v[70:71]
	v_add_f32_e32 v60, v60, v61
	v_add_f32_e32 v61, v68, v69
	ds_bpermute_b32 v62, v35, v60
	ds_bpermute_b32 v63, v35, v61
	s_waitcnt lgkmcnt(0)
	v_pk_add_f32 v[60:61], v[60:61], v[62:63]
	ds_bpermute_b32 v62, v36, v60
	ds_bpermute_b32 v63, v36, v61
	s_waitcnt lgkmcnt(0)
	v_pk_add_f32 v[60:61], v[60:61], v[62:63]
	ds_bpermute_b32 v62, v37, v60
	ds_bpermute_b32 v63, v37, v61
	s_waitcnt lgkmcnt(0)
	v_pk_add_f32 v[60:61], v[60:61], v[62:63]
	ds_bpermute_b32 v62, v38, v60
	ds_bpermute_b32 v63, v38, v61
	s_waitcnt lgkmcnt(0)
	v_pk_add_f32 v[60:61], v[60:61], v[62:63]
	ds_bpermute_b32 v62, v39, v60
	ds_bpermute_b32 v63, v39, v61
	s_waitcnt lgkmcnt(0)
	v_pk_add_f32 v[60:61], v[60:61], v[62:63]
	ds_bpermute_b32 v62, v40, v60
	ds_bpermute_b32 v63, v40, v61
	s_waitcnt lgkmcnt(0)
	v_pk_add_f32 v[60:61], v[60:61], v[62:63]
	v_fma_f32 v60, v60, s10, v52
	v_fma_f32 v62, v61, s10, v52
	v_rsq_f32_e32 v60, v60
	v_rsq_f32_e32 v62, v62
	s_nop 0
	v_pk_mul_f32 v[208:209], v[208:209], v[60:61] op_sel_hi:[1,0]
	v_pk_mul_f32 v[210:211], v[210:211], v[60:61] op_sel_hi:[1,0]
	v_pk_mul_f32 v[208:209], v[14:15], v[208:209]
	v_pk_mul_f32 v[210:211], v[16:17], v[210:211]
	v_cvt_pk_bf16_f32 v18, v208, v209
	v_cvt_pk_bf16_f32 v19, v210, v211
	v_pk_mul_f32 v[212:213], v[212:213], v[60:61] op_sel_hi:[1,0]
	v_pk_mul_f32 v[214:215], v[214:215], v[60:61] op_sel_hi:[1,0]
	v_pk_mul_f32 v[212:213], v[10:11], v[212:213]
	v_pk_mul_f32 v[214:215], v[12:13], v[214:215]
	v_cvt_pk_bf16_f32 v20, v212, v213
	v_cvt_pk_bf16_f32 v21, v214, v215
	v_pk_mul_f32 v[216:217], v[216:217], v[60:61] op_sel_hi:[1,0]
	v_pk_mul_f32 v[218:219], v[218:219], v[60:61] op_sel_hi:[1,0]
	v_pk_mul_f32 v[216:217], v[6:7], v[216:217]
	v_pk_mul_f32 v[218:219], v[8:9], v[218:219]
	v_cvt_pk_bf16_f32 v22, v216, v217
	v_cvt_pk_bf16_f32 v23, v218, v219
	v_pk_mul_f32 v[220:221], v[220:221], v[60:61] op_sel_hi:[1,0]
	v_pk_mul_f32 v[222:223], v[222:223], v[60:61] op_sel_hi:[1,0]
	v_pk_mul_f32 v[220:221], v[2:3], v[220:221]
	v_pk_mul_f32 v[222:223], v[4:5], v[222:223]
	v_cvt_pk_bf16_f32 v24, v220, v221
	v_cvt_pk_bf16_f32 v25, v222, v223
	v_pk_mul_f32 v[224:225], v[224:225], v[62:63] op_sel_hi:[1,0]
	v_pk_mul_f32 v[226:227], v[226:227], v[62:63] op_sel_hi:[1,0]
	v_pk_mul_f32 v[224:225], v[14:15], v[224:225]
	v_pk_mul_f32 v[226:227], v[16:17], v[226:227]
	v_cvt_pk_bf16_f32 v26, v224, v225
	v_cvt_pk_bf16_f32 v27, v226, v227
	v_pk_mul_f32 v[228:229], v[228:229], v[62:63] op_sel_hi:[1,0]
	v_pk_mul_f32 v[230:231], v[230:231], v[62:63] op_sel_hi:[1,0]
	v_pk_mul_f32 v[228:229], v[10:11], v[228:229]
	v_pk_mul_f32 v[230:231], v[12:13], v[230:231]
	v_cvt_pk_bf16_f32 v28, v228, v229
	v_cvt_pk_bf16_f32 v29, v230, v231
	v_pk_mul_f32 v[232:233], v[232:233], v[62:63] op_sel_hi:[1,0]
	v_pk_mul_f32 v[234:235], v[234:235], v[62:63] op_sel_hi:[1,0]
	v_pk_mul_f32 v[232:233], v[6:7], v[232:233]
	v_pk_mul_f32 v[234:235], v[8:9], v[234:235]
	v_cvt_pk_bf16_f32 v30, v232, v233
	v_cvt_pk_bf16_f32 v31, v234, v235
	v_pk_mul_f32 v[236:237], v[236:237], v[62:63] op_sel_hi:[1,0]
	v_pk_mul_f32 v[238:239], v[238:239], v[62:63] op_sel_hi:[1,0]
	v_pk_mul_f32 v[236:237], v[2:3], v[236:237]
	v_pk_mul_f32 v[238:239], v[4:5], v[238:239]
	v_cvt_pk_bf16_f32 v32, v236, v237
	v_cvt_pk_bf16_f32 v33, v238, v239
	global_store_dwordx2 v46, v[18:19], s[2:3]
	global_store_dwordx2 v46, v[20:21], s[2:3] offset:512
	global_store_dwordx2 v46, v[22:23], s[2:3] offset:1024
	global_store_dwordx2 v46, v[24:25], s[2:3] offset:1536
	s_add_u32 s2, s2, 0x400000
	s_addc_u32 s3, s3, 0
	global_store_dwordx2 v46, v[26:27], s[2:3]
	global_store_dwordx2 v46, v[28:29], s[2:3] offset:512
	global_store_dwordx2 v46, v[30:31], s[2:3] offset:1024
	global_store_dwordx2 v46, v[32:33], s[2:3] offset:1536
	s_add_u32 s2, s2, 0x400000
	s_addc_u32 s3, s3, 0
	s_branch .Lrn_done
.Lrn_generic:
	s_mov_b32 s11, 0x8000
	v_cmp_gt_i32_e32 vcc, s11, v192
	s_and_saveexec_b64 s[6:7], vcc
	s_cbranch_execz .LBB0_112
	v_lshlrev_b32_e32 v18, 4, v193
	global_load_dwordx4 v[2:5], v18, s[42:43] offset:3072
	global_load_dwordx4 v[6:9], v18, s[42:43] offset:2048
	global_load_dwordx4 v[10:13], v18, s[42:43] offset:1024
	global_load_dwordx4 v[14:17], v18, s[42:43]
	v_mov_b32_e32 v19, v47
	v_mbcnt_lo_u32_b32 v1, -1, 0
	v_lshl_add_u64 v[48:49], s[36:37], 0, v[18:19]
	v_mbcnt_hi_u32_b32 v18, -1, v1
	v_and_b32_e32 v1, 64, v18
	v_add_u32_e32 v19, 64, v1
	v_xor_b32_e32 v1, 1, v18
	v_cmp_lt_i32_e32 vcc, v1, v19
	v_xor_b32_e32 v20, 2, v18
	v_lshl_add_u64 v[50:51], s[68:69], 0, v[46:47]
	v_cndmask_b32_e32 v1, v18, v1, vcc
	v_cmp_lt_i32_e32 vcc, v20, v19
	v_lshlrev_b32_e32 v1, 2, v1
	s_mov_b64 s[8:9], 0
	v_cndmask_b32_e32 v20, v18, v20, vcc
	v_lshlrev_b32_e32 v53, 2, v20
	v_xor_b32_e32 v20, 4, v18
	v_cmp_lt_i32_e32 vcc, v20, v19
	s_mov_b32 s10, 0x3a800000
	s_mov_b32 s12, 0x800000
	v_cndmask_b32_e32 v20, v18, v20, vcc
	v_lshlrev_b32_e32 v59, 2, v20
	v_xor_b32_e32 v20, 8, v18
	v_cmp_lt_i32_e32 vcc, v20, v19
	s_movk_i32 s13, 0x7fff
	v_mov_b32_e32 v52, 0x358637bd
	v_cndmask_b32_e32 v20, v18, v20, vcc
	v_lshlrev_b32_e32 v64, 2, v20
	v_xor_b32_e32 v20, 16, v18
	v_cmp_lt_i32_e32 vcc, v20, v19
	v_mov_b32_e32 v56, v192
	s_nop 0
	v_cndmask_b32_e32 v20, v18, v20, vcc
	v_lshlrev_b32_e32 v65, 2, v20
	v_xor_b32_e32 v20, 32, v18
	v_cmp_lt_i32_e32 vcc, v20, v19
	s_nop 1
	v_cndmask_b32_e32 v18, v18, v20, vcc
	v_lshlrev_b32_e32 v66, 2, v18
	s_branch .LBB0_104

.Lrn_done:
	s_movk_i32 s11, 0x1000
	v_cmp_gt_i32_e32 vcc, s11, v192
	s_and_saveexec_b64 s[6:7], vcc
	s_cbranch_execz .LBB0_123
	v_lshlrev_b32_e32 v18, 4, v193
	global_load_dwordx4 v[2:5], v18, s[54:55] offset:3072
	global_load_dwordx4 v[6:9], v18, s[54:55] offset:2048
	global_load_dwordx4 v[10:13], v18, s[54:55] offset:1024
	global_load_dwordx4 v[14:17], v18, s[54:55]
	v_mov_b32_e32 v47, 0
	v_mov_b32_e32 v19, v47
	v_mbcnt_lo_u32_b32 v1, -1, 0
	v_lshl_add_u64 v[48:49], s[38:39], 0, v[18:19]
	v_mbcnt_hi_u32_b32 v18, -1, v1
	v_and_b32_e32 v1, 64, v18
	v_add_u32_e32 v19, 64, v1
	v_xor_b32_e32 v1, 1, v18
	v_cmp_lt_i32_e32 vcc, v1, v19
	v_xor_b32_e32 v20, 2, v18
	v_lshl_add_u64 v[50:51], s[82:83], 0, v[46:47]
	v_cndmask_b32_e32 v1, v18, v1, vcc
	v_cmp_lt_i32_e32 vcc, v20, v19
	v_lshlrev_b32_e32 v1, 2, v1
	s_mov_b64 s[8:9], 0
	v_cndmask_b32_e32 v20, v18, v20, vcc
	v_lshlrev_b32_e32 v53, 2, v20
	v_xor_b32_e32 v20, 4, v18
	v_cmp_lt_i32_e32 vcc, v20, v19
	s_mov_b32 s10, 0x3a800000
	s_mov_b32 s12, 0x800000
	v_cndmask_b32_e32 v20, v18, v20, vcc
	v_lshlrev_b32_e32 v59, 2, v20
	v_xor_b32_e32 v20, 8, v18
	v_cmp_lt_i32_e32 vcc, v20, v19
	s_movk_i32 s13, 0xfff
	v_mov_b32_e32 v52, 0x358637bd
	v_cndmask_b32_e32 v20, v18, v20, vcc
	v_lshlrev_b32_e32 v64, 2, v20
	v_xor_b32_e32 v20, 16, v18
	v_cmp_lt_i32_e32 vcc, v20, v19
	v_mov_b32_e32 v56, v192
	s_nop 0
	v_cndmask_b32_e32 v20, v18, v20, vcc
	v_lshlrev_b32_e32 v65, 2, v20
	v_xor_b32_e32 v20, 32, v18
	v_cmp_lt_i32_e32 vcc, v20, v19
	s_nop 1
	v_cndmask_b32_e32 v18, v18, v20, vcc
	v_lshlrev_b32_e32 v66, 2, v18
	s_branch .LBB0_115
